# sliding-window deferred-max loop: PV V^T fragment reads software-pipelined (7 fragments in flight, counted lgkmcnt), as already done for the selected-block loop
# speedup vs baseline: 1.0082x; 1.0082x over previous
; #define LAS __attribute__((address_space(3)))
; __device__ __forceinline__ u32x4 pack8(const f32x4 a, const f32x4 b) { u32x4 w; w.x = cvt_pk_bf16(a[0], a[1]); w.y = cvt_pk_bf16(a[2], a[3]); w.z = cvt_pk_bf16(b[0], b[1]); w.w = cvt_pk_bf16(b[2], b[3]); return w; }
; __device__ __forceinline__ void pv_tile2(f32x4 (&o)[2][8], const u32x4 (&pk)[2][2], const LAS unsigned char* buf, int ql, int g) {
; #pragma unroll
;     for (int ch = 0; ch < 2; ++ch) {
;         const bf16x8 pf0 = __builtin_bit_cast(bf16x8, pk[0][ch]), pf1 = __builtin_bit_cast(bf16x8, pk[1][ch]);
; #pragma unroll
;         for (int dt = 0; dt < 8; ++dt) {
;             const LAS unsigned char* rowp = buf + KB_BYTES + (16 * dt + ql) * VT_PITCH + (32 * ch + 4 * g) * 2;
;             const u32x2 lo = *(const LAS u32x2*)(rowp), hi = *(const LAS u32x2*)(rowp + 32);
;             const bf16x8 vf = __builtin_bit_cast(bf16x8, (u32x4){lo.x, lo.y, hi.x, hi.y});
;             o[0][dt] = __builtin_amdgcn_mfma_f32_16x16x32_bf16(vf, pf0, o[0][dt], 0, 0, 0);
;             o[1][dt] = __builtin_amdgcn_mfma_f32_16x16x32_bf16(vf, pf1, o[1][dt], 0, 0, 0);
;             if ((dt & 3) == 3) asm volatile("" ::: "memory");
;         }
;     }
; }
; template <int MODE, bool DEFER> ...
;     ...
; #pragma unroll
;         for (int gp = 0; gp < 2; ++gp) {
;             float ps = 0.f;
; #pragma unroll
;             for (int sub = 0; sub < 4; ++sub)
; #pragma unroll
;                 for (int e = 0; e < 4; ++e) { const float pv = __builtin_amdgcn_exp2f(s[gp][sub][e]); s[gp][sub][e] = pv; ps += pv; }
;             lsum[gp] += ps;
;             pk[gp][0] = pack8(s[gp][0], s[gp][1]); pk[gp][1] = pack8(s[gp][2], s[gp][3]);
;         }
;     } else {
; #pragma unroll
;         for (int gp = 0; gp < 2; ++gp) {
;             int rel, lowrel = -1000000;
;             if (MODE == 0) rel = ((t[gp] - 31) >> 4) - tile * 64 - 4 * g;
;             else { rel = t[gp] - tile * 64 - 4 * g; if (MODE == 2) lowrel = rel - 512; }
;             softmax_tile<false>(s[gp], o[gp], pk[gp], mrun[gp], lsum[gp], take[gp], rel, lowrel);
;         }
;     }
;     pv_tile2(o, pk, buf, ql, g);
;     if (tile < tile_hi) stage_store<true, true>(R, lds + ((tile + 1) & 1) * BUF_BYTES, tid);
;     __syncthreads();
.LBB0_1031:
	v_exp_f32_e32 v3, v144
	v_exp_f32_e32 v2, v128
	v_exp_f32_e32 v145, v145
	v_exp_f32_e32 v144, v129
	v_exp_f32_e32 v177, v146
	v_exp_f32_e32 v176, v130
	v_exp_f32_e32 v147, v147
	v_exp_f32_e32 v146, v131
	v_exp_f32_e32 v179, v140
	v_exp_f32_e32 v178, v124
	v_exp_f32_e32 v182, v120
	v_exp_f32_e32 v184, v121
	v_pk_add_f32 v[120:121], v[2:3], 0 op_sel_hi:[1,0]
	v_exp_f32_e32 v141, v141
	v_exp_f32_e32 v140, v125
	v_pk_add_f32 v[120:121], v[144:145], v[120:121]
	v_exp_f32_e32 v181, v142
	v_exp_f32_e32 v180, v126
	v_pk_add_f32 v[120:121], v[176:177], v[120:121]
	v_exp_f32_e32 v143, v143
	v_exp_f32_e32 v142, v127
	v_pk_add_f32 v[120:121], v[146:147], v[120:121]
	v_exp_f32_e32 v183, v136
	v_pk_add_f32 v[120:121], v[178:179], v[120:121]
	v_exp_f32_e32 v185, v137
	v_pk_add_f32 v[120:121], v[140:141], v[120:121]
	v_exp_f32_e32 v187, v138
	v_pk_add_f32 v[120:121], v[180:181], v[120:121]
	v_exp_f32_e32 v186, v122
	v_exp_f32_e32 v189, v139
	v_pk_add_f32 v[120:121], v[142:143], v[120:121]
	v_exp_f32_e32 v188, v123
	v_exp_f32_e32 v191, v132
	v_pk_add_f32 v[120:121], v[182:183], v[120:121]
	v_exp_f32_e32 v190, v116
	v_exp_f32_e32 v193, v133
	v_pk_add_f32 v[120:121], v[184:185], v[120:121]
	v_exp_f32_e32 v192, v117
	v_exp_f32_e32 v197, v134
	v_exp_f32_e32 v196, v118
	v_pk_add_f32 v[116:117], v[186:187], v[120:121]
	v_exp_f32_e32 v199, v135
	v_exp_f32_e32 v198, v119
	v_pk_add_f32 v[116:117], v[188:189], v[116:117]
	v_add3_u32 v0, s8, v148, v204
	v_pk_add_f32 v[116:117], v[190:191], v[116:117]
	v_cvt_pk_bf16_f32 v136, v3, v145
	v_cvt_pk_bf16_f32 v137, v177, v147
	v_cvt_pk_bf16_f32 v138, v179, v141
	v_cvt_pk_bf16_f32 v139, v181, v143
	v_cvt_pk_bf16_f32 v132, v183, v185
	s_nop 0
	v_pk_add_f32 v[116:117], v[192:193], v[116:117]
	v_cvt_pk_bf16_f32 v133, v187, v189
	v_cvt_pk_bf16_f32 v134, v191, v193
	v_cvt_pk_bf16_f32 v135, v197, v199
	v_cvt_pk_bf16_f32 v120, v2, v144
	v_add_u32_e32 v2, 0x4000, v0
	v_pk_add_f32 v[116:117], v[196:197], v[116:117]
	v_cvt_pk_bf16_f32 v121, v176, v146
	v_cvt_pk_bf16_f32 v122, v178, v140
	v_cvt_pk_bf16_f32 v123, v180, v142
	v_add_u32_e32 v3, 0x4800, v0
	v_pk_add_f32 v[116:117], v[198:199], v[116:117]
	v_add_u32_e32 v128, 0x5000, v0
	v_pk_add_f32 v[170:171], v[170:171], v[116:117]
	v_cvt_pk_bf16_f32 v116, v182, v184
	v_cvt_pk_bf16_f32 v117, v186, v188
	v_cvt_pk_bf16_f32 v118, v190, v192
	v_cvt_pk_bf16_f32 v119, v196, v198
	ds_read_b64 v[124:125], v0 offset:17408
	ds_read_b64 v[126:127], v0 offset:17440
	ds_read_b64 v[128:129], v0 offset:19712
	ds_read_b64 v[130:131], v0 offset:19744
	ds_read_b64 v[140:141], v0 offset:22016
	ds_read_b64 v[142:143], v0 offset:22048
	ds_read_b64 v[144:145], v0 offset:24320
	ds_read_b64 v[146:147], v0 offset:24352
	ds_read_b64 v[176:177], v0 offset:26624
	ds_read_b64 v[178:179], v0 offset:26656
	ds_read_b64 v[180:181], v0 offset:28928
	ds_read_b64 v[182:183], v0 offset:28960
	ds_read_b64 v[184:185], v0 offset:31232
	ds_read_b64 v[186:187], v0 offset:31264
	s_andn2_b32 s7, 1, s1
	s_mul_i32 s7, s7, 0x8c00
	s_add_i32 s7, s7, 0
	s_add_i32 s1, s1, 1
	s_add_i32 s6, s6, 64
	s_cmp_ge_i32 s1, s0
	s_waitcnt lgkmcnt(12)
	v_mfma_f32_16x16x32_bf16 v[96:99], v[124:127], v[136:139], v[96:99]
	v_mfma_f32_16x16x32_bf16 v[64:67], v[124:127], v[120:123], v[64:67]
	ds_read_b64 v[188:189], v0 offset:33536
	ds_read_b64 v[190:191], v0 offset:33568
	s_waitcnt lgkmcnt(12)
	v_mfma_f32_16x16x32_bf16 v[92:95], v[128:131], v[136:139], v[92:95]
	v_mfma_f32_16x16x32_bf16 v[60:63], v[128:131], v[120:123], v[60:63]
	ds_read_b64 v[124:125], v0 offset:17472
	ds_read_b64 v[126:127], v0 offset:17504
	s_waitcnt lgkmcnt(12)
	v_mfma_f32_16x16x32_bf16 v[88:91], v[140:143], v[136:139], v[88:91]
	v_mfma_f32_16x16x32_bf16 v[56:59], v[140:143], v[120:123], v[56:59]
	ds_read_b64 v[128:129], v0 offset:19776
	ds_read_b64 v[130:131], v0 offset:19808
	s_waitcnt lgkmcnt(12)
	v_mfma_f32_16x16x32_bf16 v[84:87], v[144:147], v[136:139], v[84:87]
	v_mfma_f32_16x16x32_bf16 v[52:55], v[144:147], v[120:123], v[52:55]
	ds_read_b64 v[140:141], v0 offset:22080
	ds_read_b64 v[142:143], v0 offset:22112
	s_waitcnt lgkmcnt(12)
	v_mfma_f32_16x16x32_bf16 v[80:83], v[176:179], v[136:139], v[80:83]
	v_mfma_f32_16x16x32_bf16 v[48:51], v[176:179], v[120:123], v[48:51]
	ds_read_b64 v[144:145], v0 offset:24384
	ds_read_b64 v[146:147], v0 offset:24416
	s_waitcnt lgkmcnt(12)
	v_mfma_f32_16x16x32_bf16 v[76:79], v[180:183], v[136:139], v[76:79]
	v_mfma_f32_16x16x32_bf16 v[44:47], v[180:183], v[120:123], v[44:47]
	ds_read_b64 v[176:177], v0 offset:26688
	ds_read_b64 v[178:179], v0 offset:26720
	s_waitcnt lgkmcnt(12)
	v_mfma_f32_16x16x32_bf16 v[68:71], v[184:187], v[136:139], v[68:71]
	v_mfma_f32_16x16x32_bf16 v[36:39], v[184:187], v[120:123], v[36:39]
	ds_read_b64 v[180:181], v0 offset:28992
	ds_read_b64 v[182:183], v0 offset:29024
	s_waitcnt lgkmcnt(12)
	v_mfma_f32_16x16x32_bf16 v[72:75], v[188:191], v[136:139], v[72:75]
	v_mfma_f32_16x16x32_bf16 v[40:43], v[188:191], v[120:123], v[40:43]
	ds_read_b64 v[184:185], v0 offset:31296
	ds_read_b64 v[186:187], v0 offset:31328
	s_waitcnt lgkmcnt(12)
	v_mfma_f32_16x16x32_bf16 v[96:99], v[124:127], v[132:135], v[96:99]
	v_mfma_f32_16x16x32_bf16 v[64:67], v[124:127], v[116:119], v[64:67]
	ds_read_b64 v[188:189], v0 offset:33600
	ds_read_b64 v[190:191], v0 offset:33632
	s_waitcnt lgkmcnt(12)
	v_mfma_f32_16x16x32_bf16 v[92:95], v[128:131], v[132:135], v[92:95]
	v_mfma_f32_16x16x32_bf16 v[60:63], v[128:131], v[116:119], v[60:63]
	s_waitcnt lgkmcnt(10)
	v_mfma_f32_16x16x32_bf16 v[88:91], v[140:143], v[132:135], v[88:91]
	v_mfma_f32_16x16x32_bf16 v[56:59], v[140:143], v[116:119], v[56:59]
	s_waitcnt lgkmcnt(8)
	v_mfma_f32_16x16x32_bf16 v[84:87], v[144:147], v[132:135], v[84:87]
	v_mfma_f32_16x16x32_bf16 v[52:55], v[144:147], v[116:119], v[52:55]
	s_waitcnt lgkmcnt(6)
	v_mfma_f32_16x16x32_bf16 v[80:83], v[176:179], v[132:135], v[80:83]
	v_mfma_f32_16x16x32_bf16 v[48:51], v[176:179], v[116:119], v[48:51]
	s_waitcnt lgkmcnt(4)
	v_mfma_f32_16x16x32_bf16 v[76:79], v[180:183], v[132:135], v[76:79]
	v_mfma_f32_16x16x32_bf16 v[44:47], v[180:183], v[116:119], v[44:47]
	s_waitcnt lgkmcnt(2)
	v_mfma_f32_16x16x32_bf16 v[68:71], v[184:187], v[132:135], v[68:71]
	v_mfma_f32_16x16x32_bf16 v[36:39], v[184:187], v[116:119], v[36:39]
	s_waitcnt lgkmcnt(0)
	v_mfma_f32_16x16x32_bf16 v[72:75], v[188:191], v[132:135], v[72:75]
	v_mfma_f32_16x16x32_bf16 v[40:43], v[188:191], v[116:119], v[40:43]
	v_add_u32_e32 v2, s7, v206
	v_add_u32_e32 v0, s7, v205
	v_add_u32_e32 v3, v0, v207
	v_add_u32_e32 v0, v0, v209
	v_add_u32_e32 v116, v2, v208
	v_add_u32_e32 v2, v2, v210
	s_waitcnt vmcnt(2)
	ds_write_b128 v3, v[100:103]
	s_waitcnt vmcnt(1)
	ds_write_b128 v116, v[104:107] offset:17408
	ds_write_b128 v0, v[108:111]
	s_waitcnt vmcnt(0)
	ds_write_b128 v2, v[112:115] offset:17408
	s_waitcnt lgkmcnt(0)
	s_barrier
	s_cbranch_scc1 .LBB0_1034
